# barrier trims + P1 and P5 split-K fix-ups: all 16 partial pieces loaded up front (one round trip instead of 16 / 10)
# speedup vs baseline: 1.0133x; 1.0133x over previous
.LBB0_388:
	v_add_u32_e32 v2, s97, v194
	v_readlane_b32 s2, v255, 1
	v_ashrrev_i32_e32 v3, 31, v2
	v_readlane_b32 s3, v255, 2
	s_and_b64 vcc, exec, s[70:71]
	s_waitcnt vmcnt(0) lgkmcnt(0)
	v_lshl_add_u64 v[124:125], v[2:3], 4, s[2:3]
	s_barrier
	v_readlane_b32 s100, v255, 33
	s_nop 3
	s_and_b32 s100, s100, 3
	s_lshl_b32 s100, s100, 11
	s_mov_b32 s101, 0
	v_lshl_add_u64 v[248:249], s[100:101], 0, v[124:125]
	global_load_dwordx4 v[168:171], v[248:249], off
	global_load_dwordx4 v[200:203], v[248:249], off offset:1024
	s_mov_b32 s100, 0x20000
	v_lshl_add_u64 v[250:251], s[100:101], 0, v[248:249]
	global_load_dwordx4 v[172:175], v[250:251], off
	global_load_dwordx4 v[204:207], v[250:251], off offset:1024
	s_mov_b32 s100, 0x40000
	v_lshl_add_u64 v[250:251], s[100:101], 0, v[248:249]
	global_load_dwordx4 v[176:179], v[250:251], off
	global_load_dwordx4 v[208:211], v[250:251], off offset:1024
	s_mov_b32 s100, 0x60000
	v_lshl_add_u64 v[250:251], s[100:101], 0, v[248:249]
	global_load_dwordx4 v[180:183], v[250:251], off
	global_load_dwordx4 v[212:215], v[250:251], off offset:1024
	s_mov_b32 s100, 0x2000
	v_lshl_add_u64 v[250:251], s[100:101], 0, v[248:249]
	global_load_dwordx4 v[216:219], v[250:251], off
	global_load_dwordx4 v[232:235], v[250:251], off offset:1024
	s_mov_b32 s100, 0x22000
	v_lshl_add_u64 v[250:251], s[100:101], 0, v[248:249]
	global_load_dwordx4 v[220:223], v[250:251], off
	global_load_dwordx4 v[236:239], v[250:251], off offset:1024
	s_mov_b32 s100, 0x42000
	v_lshl_add_u64 v[250:251], s[100:101], 0, v[248:249]
	global_load_dwordx4 v[224:227], v[250:251], off
	global_load_dwordx4 v[240:243], v[250:251], off offset:1024
	s_mov_b32 s100, 0x62000
	v_lshl_add_u64 v[250:251], s[100:101], 0, v[248:249]
	global_load_dwordx4 v[228:231], v[250:251], off
	global_load_dwordx4 v[244:247], v[250:251], off offset:1024
	s_waitcnt vmcnt(0)
	s_cbranch_vccnz .LBB0_392
	v_mov_b32_e32 v2, v0
	v_mov_b32_e32 v3, v0
	v_mov_b32_e32 v1, v0
	v_mov_b64_e32 v[6:7], v[2:3]
	v_mov_b64_e32 v[10:11], v[2:3]
	v_mov_b64_e32 v[4:5], v[0:1]
	v_mov_b64_e32 v[8:9], v[0:1]
	v_cndmask_b32_e64 v1, 0, 1, s[70:71]
	v_cmp_ne_u32_e64 s[2:3], 1, v1
	s_andn2_b64 vcc, exec, s[70:71]
	s_cbranch_vccz .LBB0_393

.LBB0_392:
	s_mov_b32 s2, 0x20000
	v_lshlrev_b32_e32 v6, 16, v168
	v_and_b32_e32 v7, 0xffff0000, v168
	v_lshlrev_b32_e32 v2, 16, v169
	v_and_b32_e32 v3, 0xffff0000, v169
	v_pk_add_f32 v[8:9], v[2:3], 0 op_sel_hi:[1, 0]
	v_lshlrev_b32_e32 v2, 16, v170
	v_and_b32_e32 v3, 0xffff0000, v170
	v_pk_add_f32 v[10:11], v[2:3], 0 op_sel_hi:[1, 0]
	v_lshlrev_b32_e32 v4, 16, v171
	v_and_b32_e32 v5, 0xffff0000, v171
	v_pk_add_f32 v[12:13], v[4:5], 0 op_sel_hi:[1, 0]
	s_mov_b32 s2, 0x40000
	v_pk_add_f32 v[6:7], v[6:7], 0 op_sel_hi:[1, 0]
	v_lshlrev_b32_e32 v14, 16, v172
	v_and_b32_e32 v15, 0xffff0000, v172
	v_lshlrev_b32_e32 v2, 16, v173
	v_and_b32_e32 v3, 0xffff0000, v173
	v_pk_add_f32 v[8:9], v[8:9], v[2:3]
	v_lshlrev_b32_e32 v2, 16, v174
	v_and_b32_e32 v3, 0xffff0000, v174
	v_pk_add_f32 v[10:11], v[10:11], v[2:3]
	v_lshlrev_b32_e32 v4, 16, v175
	v_and_b32_e32 v5, 0xffff0000, v175
	v_pk_add_f32 v[12:13], v[12:13], v[4:5]
	v_pk_add_f32 v[6:7], v[6:7], v[14:15]
	s_mov_b32 s2, 0x60000
	v_lshlrev_b32_e32 v14, 16, v176
	v_and_b32_e32 v15, 0xffff0000, v176
	v_pk_add_f32 v[14:15], v[6:7], v[14:15]
	v_lshlrev_b32_e32 v6, 16, v178
	v_and_b32_e32 v7, 0xffff0000, v178
	v_lshlrev_b32_e32 v4, 16, v179
	v_and_b32_e32 v5, 0xffff0000, v179
	v_pk_add_f32 v[16:17], v[10:11], v[6:7]
	v_pk_add_f32 v[10:11], v[12:13], v[4:5]
	v_lshlrev_b32_e32 v2, 16, v177
	v_and_b32_e32 v3, 0xffff0000, v177
	v_pk_add_f32 v[2:3], v[8:9], v[2:3]
	v_lshlrev_b32_e32 v4, 16, v180
	v_and_b32_e32 v5, 0xffff0000, v180
	v_lshlrev_b32_e32 v6, 16, v181
	v_and_b32_e32 v7, 0xffff0000, v181
	v_pk_add_f32 v[6:7], v[2:3], v[6:7]
	v_lshlrev_b32_e32 v2, 16, v182
	v_and_b32_e32 v3, 0xffff0000, v182
	v_lshlrev_b32_e32 v8, 16, v183
	v_and_b32_e32 v9, 0xffff0000, v183
	v_pk_add_f32 v[4:5], v[14:15], v[4:5]
	v_pk_add_f32 v[10:11], v[10:11], v[8:9]
	v_pk_add_f32 v[8:9], v[16:17], v[2:3]
	v_cndmask_b32_e64 v1, 0, 1, s[70:71]
	v_cmp_ne_u32_e64 s[2:3], 1, v1
	s_andn2_b64 vcc, exec, s[70:71]
	s_cbranch_vccnz .LBB0_390
.LBB0_393:
	s_mov_b32 s4, 0x20000
	v_lshlrev_b32_e32 v2, 16, v200
	v_and_b32_e32 v3, 0xffff0000, v200
	v_lshlrev_b32_e32 v12, 16, v201
	v_and_b32_e32 v13, 0xffff0000, v201
	v_pk_add_f32 v[16:17], v[12:13], 0 op_sel_hi:[1, 0]
	v_lshlrev_b32_e32 v12, 16, v202
	v_and_b32_e32 v13, 0xffff0000, v202
	v_pk_add_f32 v[18:19], v[12:13], 0 op_sel_hi:[1, 0]
	v_lshlrev_b32_e32 v14, 16, v203
	v_and_b32_e32 v15, 0xffff0000, v203
	v_pk_add_f32 v[20:21], v[14:15], 0 op_sel_hi:[1, 0]
	s_mov_b32 s4, 0x40000
	v_pk_add_f32 v[2:3], v[2:3], 0 op_sel_hi:[1, 0]
	v_lshlrev_b32_e32 v22, 16, v204
	v_and_b32_e32 v23, 0xffff0000, v204
	v_lshlrev_b32_e32 v12, 16, v205
	v_and_b32_e32 v13, 0xffff0000, v205
	v_pk_add_f32 v[16:17], v[16:17], v[12:13]
	v_lshlrev_b32_e32 v12, 16, v206
	v_and_b32_e32 v13, 0xffff0000, v206
	v_pk_add_f32 v[18:19], v[18:19], v[12:13]
	v_lshlrev_b32_e32 v14, 16, v207
	v_and_b32_e32 v15, 0xffff0000, v207
	v_pk_add_f32 v[20:21], v[20:21], v[14:15]
	v_pk_add_f32 v[2:3], v[2:3], v[22:23]
	s_mov_b32 s4, 0x60000
	v_lshlrev_b32_e32 v22, 16, v208
	v_and_b32_e32 v23, 0xffff0000, v208
	v_lshlrev_b32_e32 v12, 16, v209
	v_and_b32_e32 v13, 0xffff0000, v209
	v_pk_add_f32 v[12:13], v[16:17], v[12:13]
	v_lshlrev_b32_e32 v16, 16, v210
	v_and_b32_e32 v17, 0xffff0000, v210
	v_lshlrev_b32_e32 v14, 16, v211
	v_and_b32_e32 v15, 0xffff0000, v211
	v_pk_add_f32 v[2:3], v[2:3], v[22:23]
	v_pk_add_f32 v[22:23], v[18:19], v[16:17]
	v_pk_add_f32 v[18:19], v[20:21], v[14:15]
	v_lshlrev_b32_e32 v20, 16, v212
	v_and_b32_e32 v21, 0xffff0000, v212
	v_lshlrev_b32_e32 v14, 16, v213
	v_and_b32_e32 v15, 0xffff0000, v213
	v_pk_add_f32 v[14:15], v[12:13], v[14:15]
	v_pk_add_f32 v[12:13], v[2:3], v[20:21]
	v_lshlrev_b32_e32 v2, 16, v214
	v_and_b32_e32 v3, 0xffff0000, v214
	v_lshlrev_b32_e32 v16, 16, v215
	v_and_b32_e32 v17, 0xffff0000, v215
	v_pk_add_f32 v[18:19], v[18:19], v[16:17]
	v_pk_add_f32 v[16:17], v[22:23], v[2:3]
.LBB0_394:
	v_readlane_b32 s6, v255, 3
	v_readlane_b32 s7, v255, 4
	s_andn2_b64 vcc, exec, s[6:7]
	s_nop 0
	v_cndmask_b32_e64 v1, 0, 1, s[6:7]
	v_cmp_ne_u32_e64 s[4:5], 1, v1
	s_cbranch_vccnz .LBB0_397
	s_mov_b32 s6, 0x20000
	v_lshlrev_b32_e32 v2, 16, v168
	v_and_b32_e32 v3, 0xffff0000, v168
	v_lshlrev_b32_e32 v20, 16, v169
	v_and_b32_e32 v21, 0xffff0000, v169
	v_pk_add_f32 v[24:25], v[20:21], 0 op_sel_hi:[1, 0]
	v_lshlrev_b32_e32 v20, 16, v170
	v_and_b32_e32 v21, 0xffff0000, v170
	v_pk_add_f32 v[26:27], v[20:21], 0 op_sel_hi:[1, 0]
	v_lshlrev_b32_e32 v22, 16, v171
	v_and_b32_e32 v23, 0xffff0000, v171
	v_pk_add_f32 v[28:29], v[22:23], 0 op_sel_hi:[1, 0]
	s_mov_b32 s6, 0x40000
	v_pk_add_f32 v[2:3], v[2:3], 0 op_sel_hi:[1, 0]
	v_lshlrev_b32_e32 v30, 16, v172
	v_and_b32_e32 v31, 0xffff0000, v172
	v_lshlrev_b32_e32 v20, 16, v173
	v_and_b32_e32 v21, 0xffff0000, v173
	v_pk_add_f32 v[24:25], v[24:25], v[20:21]
	v_lshlrev_b32_e32 v20, 16, v174
	v_and_b32_e32 v21, 0xffff0000, v174
	v_pk_add_f32 v[26:27], v[26:27], v[20:21]
	v_lshlrev_b32_e32 v22, 16, v175
	v_and_b32_e32 v23, 0xffff0000, v175
	v_pk_add_f32 v[28:29], v[28:29], v[22:23]
	v_pk_add_f32 v[2:3], v[2:3], v[30:31]
	s_mov_b32 s6, 0x60000
	v_lshlrev_b32_e32 v30, 16, v176
	v_and_b32_e32 v31, 0xffff0000, v176
	v_lshlrev_b32_e32 v20, 16, v177
	v_and_b32_e32 v21, 0xffff0000, v177
	v_pk_add_f32 v[20:21], v[24:25], v[20:21]
	v_lshlrev_b32_e32 v24, 16, v178
	v_and_b32_e32 v25, 0xffff0000, v178
	v_lshlrev_b32_e32 v22, 16, v179
	v_and_b32_e32 v23, 0xffff0000, v179
	v_pk_add_f32 v[2:3], v[2:3], v[30:31]
	v_pk_add_f32 v[30:31], v[26:27], v[24:25]
	v_pk_add_f32 v[26:27], v[28:29], v[22:23]
	v_lshlrev_b32_e32 v28, 16, v180
	v_and_b32_e32 v29, 0xffff0000, v180
	v_lshlrev_b32_e32 v22, 16, v181
	v_and_b32_e32 v23, 0xffff0000, v181
	v_pk_add_f32 v[22:23], v[20:21], v[22:23]
	v_pk_add_f32 v[20:21], v[2:3], v[28:29]
	v_lshlrev_b32_e32 v2, 16, v182
	v_and_b32_e32 v3, 0xffff0000, v182
	v_lshlrev_b32_e32 v24, 16, v183
	v_and_b32_e32 v25, 0xffff0000, v183
	v_pk_add_f32 v[26:27], v[26:27], v[24:25]
	v_pk_add_f32 v[24:25], v[30:31], v[2:3]
	s_and_b64 vcc, exec, s[4:5]
	s_cbranch_vccz .LBB0_398

.LBB0_398:
	s_mov_b32 s6, 0x20000
	v_lshlrev_b32_e32 v2, 16, v200
	v_and_b32_e32 v3, 0xffff0000, v200
	v_lshlrev_b32_e32 v28, 16, v201
	v_and_b32_e32 v29, 0xffff0000, v201
	v_pk_add_f32 v[32:33], v[28:29], 0 op_sel_hi:[1, 0]
	v_lshlrev_b32_e32 v28, 16, v202
	v_and_b32_e32 v29, 0xffff0000, v202
	v_pk_add_f32 v[34:35], v[28:29], 0 op_sel_hi:[1, 0]
	v_lshlrev_b32_e32 v30, 16, v203
	v_and_b32_e32 v31, 0xffff0000, v203
	v_pk_add_f32 v[36:37], v[30:31], 0 op_sel_hi:[1, 0]
	s_mov_b32 s6, 0x40000
	v_pk_add_f32 v[2:3], v[2:3], 0 op_sel_hi:[1, 0]
	v_lshlrev_b32_e32 v38, 16, v204
	v_and_b32_e32 v39, 0xffff0000, v204
	v_lshlrev_b32_e32 v28, 16, v205
	v_and_b32_e32 v29, 0xffff0000, v205
	v_pk_add_f32 v[32:33], v[32:33], v[28:29]
	v_lshlrev_b32_e32 v28, 16, v206
	v_and_b32_e32 v29, 0xffff0000, v206
	v_pk_add_f32 v[34:35], v[34:35], v[28:29]
	v_lshlrev_b32_e32 v30, 16, v207
	v_and_b32_e32 v31, 0xffff0000, v207
	v_pk_add_f32 v[36:37], v[36:37], v[30:31]
	v_pk_add_f32 v[2:3], v[2:3], v[38:39]
	s_mov_b32 s6, 0x60000
	v_lshlrev_b32_e32 v38, 16, v208
	v_and_b32_e32 v39, 0xffff0000, v208
	v_lshlrev_b32_e32 v28, 16, v209
	v_and_b32_e32 v29, 0xffff0000, v209
	v_pk_add_f32 v[28:29], v[32:33], v[28:29]
	v_lshlrev_b32_e32 v32, 16, v210
	v_and_b32_e32 v33, 0xffff0000, v210
	v_lshlrev_b32_e32 v30, 16, v211
	v_and_b32_e32 v31, 0xffff0000, v211
	v_pk_add_f32 v[2:3], v[2:3], v[38:39]
	v_pk_add_f32 v[38:39], v[34:35], v[32:33]
	v_pk_add_f32 v[34:35], v[36:37], v[30:31]
	v_lshlrev_b32_e32 v36, 16, v212
	v_and_b32_e32 v37, 0xffff0000, v212
	v_lshlrev_b32_e32 v30, 16, v213
	v_and_b32_e32 v31, 0xffff0000, v213
	v_pk_add_f32 v[30:31], v[28:29], v[30:31]
	v_pk_add_f32 v[28:29], v[2:3], v[36:37]
	v_lshlrev_b32_e32 v2, 16, v214
	v_and_b32_e32 v3, 0xffff0000, v214
	v_lshlrev_b32_e32 v32, 16, v215
	v_and_b32_e32 v33, 0xffff0000, v215
	v_pk_add_f32 v[34:35], v[34:35], v[32:33]
	v_pk_add_f32 v[32:33], v[38:39], v[2:3]
.LBB0_399:
	v_readlane_b32 s8, v255, 5
	v_readlane_b32 s9, v255, 6
	s_andn2_b64 vcc, exec, s[8:9]
	s_nop 0
	v_cndmask_b32_e64 v1, 0, 1, s[8:9]
	v_cmp_ne_u32_e64 s[6:7], 1, v1
	s_cbranch_vccnz .LBB0_402
	v_lshlrev_b32_e32 v2, 16, v168
	v_and_b32_e32 v3, 0xffff0000, v168
	v_lshlrev_b32_e32 v36, 16, v169
	v_and_b32_e32 v37, 0xffff0000, v169
	v_pk_add_f32 v[40:41], v[36:37], 0 op_sel_hi:[1, 0]
	v_lshlrev_b32_e32 v36, 16, v170
	v_and_b32_e32 v37, 0xffff0000, v170
	v_pk_add_f32 v[42:43], v[36:37], 0 op_sel_hi:[1, 0]
	v_lshlrev_b32_e32 v38, 16, v171
	v_and_b32_e32 v39, 0xffff0000, v171
	v_pk_add_f32 v[44:45], v[38:39], 0 op_sel_hi:[1, 0]
	v_pk_add_f32 v[2:3], v[2:3], 0 op_sel_hi:[1, 0]
	v_lshlrev_b32_e32 v46, 16, v172
	v_and_b32_e32 v47, 0xffff0000, v172
	v_lshlrev_b32_e32 v36, 16, v173
	v_and_b32_e32 v37, 0xffff0000, v173
	v_pk_add_f32 v[40:41], v[40:41], v[36:37]
	v_lshlrev_b32_e32 v36, 16, v174
	v_and_b32_e32 v37, 0xffff0000, v174
	v_pk_add_f32 v[42:43], v[42:43], v[36:37]
	v_lshlrev_b32_e32 v38, 16, v175
	v_and_b32_e32 v39, 0xffff0000, v175
	v_pk_add_f32 v[44:45], v[44:45], v[38:39]
	v_pk_add_f32 v[2:3], v[2:3], v[46:47]
	v_lshlrev_b32_e32 v46, 16, v176
	v_and_b32_e32 v47, 0xffff0000, v176
	v_lshlrev_b32_e32 v36, 16, v177
	v_and_b32_e32 v37, 0xffff0000, v177
	v_pk_add_f32 v[46:47], v[2:3], v[46:47]
	v_lshlrev_b32_e32 v2, 16, v178
	v_and_b32_e32 v3, 0xffff0000, v178
	v_lshlrev_b32_e32 v38, 16, v179
	v_and_b32_e32 v39, 0xffff0000, v179
	v_pk_add_f32 v[36:37], v[40:41], v[36:37]
	v_pk_add_f32 v[40:41], v[44:45], v[38:39]
	v_pk_add_f32 v[2:3], v[42:43], v[2:3]
	v_lshlrev_b32_e32 v48, 16, v180
	v_and_b32_e32 v49, 0xffff0000, v180
	v_lshlrev_b32_e32 v38, 16, v181
	v_and_b32_e32 v39, 0xffff0000, v181
	v_pk_add_f32 v[38:39], v[36:37], v[38:39]
	v_pk_add_f32 v[36:37], v[46:47], v[48:49]
	v_lshlrev_b32_e32 v46, 16, v182
	v_and_b32_e32 v47, 0xffff0000, v182
	v_lshlrev_b32_e32 v42, 16, v183
	v_and_b32_e32 v43, 0xffff0000, v183
	v_pk_add_f32 v[42:43], v[40:41], v[42:43]
	v_pk_add_f32 v[40:41], v[2:3], v[46:47]
	s_and_b64 vcc, exec, s[6:7]
	s_cbranch_vccz .LBB0_403

.LBB0_403:
	v_lshlrev_b32_e32 v2, 16, v200
	v_and_b32_e32 v3, 0xffff0000, v200
	v_lshlrev_b32_e32 v44, 16, v201
	v_and_b32_e32 v45, 0xffff0000, v201
	v_pk_add_f32 v[48:49], v[44:45], 0 op_sel_hi:[1, 0]
	v_lshlrev_b32_e32 v44, 16, v202
	v_and_b32_e32 v45, 0xffff0000, v202
	v_pk_add_f32 v[50:51], v[44:45], 0 op_sel_hi:[1, 0]
	v_lshlrev_b32_e32 v46, 16, v203
	v_and_b32_e32 v47, 0xffff0000, v203
	v_pk_add_f32 v[52:53], v[46:47], 0 op_sel_hi:[1, 0]
	v_pk_add_f32 v[2:3], v[2:3], 0 op_sel_hi:[1, 0]
	v_lshlrev_b32_e32 v54, 16, v204
	v_and_b32_e32 v55, 0xffff0000, v204
	v_lshlrev_b32_e32 v44, 16, v205
	v_and_b32_e32 v45, 0xffff0000, v205
	v_pk_add_f32 v[48:49], v[48:49], v[44:45]
	v_lshlrev_b32_e32 v44, 16, v206
	v_and_b32_e32 v45, 0xffff0000, v206
	v_pk_add_f32 v[50:51], v[50:51], v[44:45]
	v_lshlrev_b32_e32 v46, 16, v207
	v_and_b32_e32 v47, 0xffff0000, v207
	v_pk_add_f32 v[52:53], v[52:53], v[46:47]
	v_pk_add_f32 v[2:3], v[2:3], v[54:55]
	v_lshlrev_b32_e32 v54, 16, v208
	v_and_b32_e32 v55, 0xffff0000, v208
	v_lshlrev_b32_e32 v44, 16, v209
	v_and_b32_e32 v45, 0xffff0000, v209
	v_pk_add_f32 v[54:55], v[2:3], v[54:55]
	v_lshlrev_b32_e32 v2, 16, v210
	v_and_b32_e32 v3, 0xffff0000, v210
	v_lshlrev_b32_e32 v46, 16, v211
	v_and_b32_e32 v47, 0xffff0000, v211
	v_pk_add_f32 v[44:45], v[48:49], v[44:45]
	v_pk_add_f32 v[48:49], v[52:53], v[46:47]
	v_pk_add_f32 v[2:3], v[50:51], v[2:3]
	v_lshlrev_b32_e32 v56, 16, v212
	v_and_b32_e32 v57, 0xffff0000, v212
	v_lshlrev_b32_e32 v46, 16, v213
	v_and_b32_e32 v47, 0xffff0000, v213
	v_pk_add_f32 v[46:47], v[44:45], v[46:47]
	v_pk_add_f32 v[44:45], v[54:55], v[56:57]
	v_lshlrev_b32_e32 v54, 16, v214
	v_and_b32_e32 v55, 0xffff0000, v214
	v_lshlrev_b32_e32 v50, 16, v215
	v_and_b32_e32 v51, 0xffff0000, v215
	v_pk_add_f32 v[50:51], v[48:49], v[50:51]
	v_pk_add_f32 v[48:49], v[2:3], v[54:55]
.LBB0_404:
	v_readlane_b32 s10, v255, 7
	v_readlane_b32 s11, v255, 8
	s_andn2_b64 vcc, exec, s[10:11]
	s_nop 0
	v_cndmask_b32_e64 v1, 0, 1, s[10:11]
	v_cmp_ne_u32_e64 s[8:9], 1, v1
	s_cbranch_vccnz .LBB0_409
	v_lshlrev_b32_e32 v2, 16, v168
	v_and_b32_e32 v3, 0xffff0000, v168
	v_lshlrev_b32_e32 v52, 16, v169
	v_and_b32_e32 v53, 0xffff0000, v169
	v_pk_add_f32 v[56:57], v[52:53], 0 op_sel_hi:[1, 0]
	v_lshlrev_b32_e32 v52, 16, v170
	v_and_b32_e32 v53, 0xffff0000, v170
	v_pk_add_f32 v[58:59], v[52:53], 0 op_sel_hi:[1, 0]
	v_lshlrev_b32_e32 v54, 16, v171
	v_and_b32_e32 v55, 0xffff0000, v171
	v_pk_add_f32 v[60:61], v[54:55], 0 op_sel_hi:[1, 0]
	v_pk_add_f32 v[2:3], v[2:3], 0 op_sel_hi:[1, 0]
	v_lshlrev_b32_e32 v62, 16, v172
	v_and_b32_e32 v63, 0xffff0000, v172
	v_lshlrev_b32_e32 v52, 16, v173
	v_and_b32_e32 v53, 0xffff0000, v173
	v_pk_add_f32 v[56:57], v[56:57], v[52:53]
	v_lshlrev_b32_e32 v52, 16, v174
	v_and_b32_e32 v53, 0xffff0000, v174
	v_pk_add_f32 v[58:59], v[58:59], v[52:53]
	v_lshlrev_b32_e32 v54, 16, v175
	v_and_b32_e32 v55, 0xffff0000, v175
	v_pk_add_f32 v[60:61], v[60:61], v[54:55]
	v_pk_add_f32 v[2:3], v[2:3], v[62:63]
	v_lshlrev_b32_e32 v62, 16, v176
	v_and_b32_e32 v63, 0xffff0000, v176
	v_lshlrev_b32_e32 v52, 16, v177
	v_and_b32_e32 v53, 0xffff0000, v177
	v_pk_add_f32 v[62:63], v[2:3], v[62:63]
	v_lshlrev_b32_e32 v2, 16, v178
	v_and_b32_e32 v3, 0xffff0000, v178
	v_lshlrev_b32_e32 v54, 16, v179
	v_and_b32_e32 v55, 0xffff0000, v179
	v_pk_add_f32 v[52:53], v[56:57], v[52:53]
	v_pk_add_f32 v[56:57], v[60:61], v[54:55]
	v_pk_add_f32 v[2:3], v[58:59], v[2:3]
	v_lshlrev_b32_e32 v64, 16, v180
	v_and_b32_e32 v65, 0xffff0000, v180
	v_lshlrev_b32_e32 v54, 16, v181
	v_and_b32_e32 v55, 0xffff0000, v181
	v_pk_add_f32 v[54:55], v[52:53], v[54:55]
	v_pk_add_f32 v[52:53], v[62:63], v[64:65]
	v_lshlrev_b32_e32 v62, 16, v182
	v_and_b32_e32 v63, 0xffff0000, v182
	v_lshlrev_b32_e32 v58, 16, v183
	v_and_b32_e32 v59, 0xffff0000, v183
	v_pk_add_f32 v[58:59], v[56:57], v[58:59]
	v_pk_add_f32 v[56:57], v[2:3], v[62:63]
	s_and_b64 vcc, exec, s[8:9]
	s_cbranch_vccz .LBB0_410

.LBB0_410:
	v_lshlrev_b32_e32 v2, 16, v200
	v_and_b32_e32 v3, 0xffff0000, v200
	v_lshlrev_b32_e32 v60, 16, v201
	v_and_b32_e32 v61, 0xffff0000, v201
	v_pk_add_f32 v[64:65], v[60:61], 0 op_sel_hi:[1, 0]
	v_lshlrev_b32_e32 v60, 16, v202
	v_and_b32_e32 v61, 0xffff0000, v202
	v_pk_add_f32 v[66:67], v[60:61], 0 op_sel_hi:[1, 0]
	v_lshlrev_b32_e32 v62, 16, v203
	v_and_b32_e32 v63, 0xffff0000, v203
	v_pk_add_f32 v[68:69], v[62:63], 0 op_sel_hi:[1, 0]
	v_pk_add_f32 v[2:3], v[2:3], 0 op_sel_hi:[1, 0]
	v_lshlrev_b32_e32 v70, 16, v204
	v_and_b32_e32 v71, 0xffff0000, v204
	v_lshlrev_b32_e32 v60, 16, v205
	v_and_b32_e32 v61, 0xffff0000, v205
	v_pk_add_f32 v[64:65], v[64:65], v[60:61]
	v_lshlrev_b32_e32 v60, 16, v206
	v_and_b32_e32 v61, 0xffff0000, v206
	v_pk_add_f32 v[66:67], v[66:67], v[60:61]
	v_lshlrev_b32_e32 v62, 16, v207
	v_and_b32_e32 v63, 0xffff0000, v207
	v_pk_add_f32 v[68:69], v[68:69], v[62:63]
	v_pk_add_f32 v[2:3], v[2:3], v[70:71]
	v_lshlrev_b32_e32 v70, 16, v208
	v_and_b32_e32 v71, 0xffff0000, v208
	v_lshlrev_b32_e32 v60, 16, v209
	v_and_b32_e32 v61, 0xffff0000, v209
	v_pk_add_f32 v[70:71], v[2:3], v[70:71]
	v_lshlrev_b32_e32 v2, 16, v210
	v_and_b32_e32 v3, 0xffff0000, v210
	v_lshlrev_b32_e32 v62, 16, v211
	v_and_b32_e32 v63, 0xffff0000, v211
	v_pk_add_f32 v[60:61], v[64:65], v[60:61]
	v_pk_add_f32 v[64:65], v[68:69], v[62:63]
	v_pk_add_f32 v[2:3], v[66:67], v[2:3]
	v_lshlrev_b32_e32 v72, 16, v212
	v_and_b32_e32 v73, 0xffff0000, v212
	v_lshlrev_b32_e32 v62, 16, v213
	v_and_b32_e32 v63, 0xffff0000, v213
	v_pk_add_f32 v[62:63], v[60:61], v[62:63]
	v_pk_add_f32 v[60:61], v[70:71], v[72:73]
	v_lshlrev_b32_e32 v70, 16, v214
	v_and_b32_e32 v71, 0xffff0000, v214
	v_lshlrev_b32_e32 v66, 16, v215
	v_and_b32_e32 v67, 0xffff0000, v215
	v_pk_add_f32 v[66:67], v[64:65], v[66:67]
	v_pk_add_f32 v[64:65], v[2:3], v[70:71]
	s_and_b64 vcc, exec, s[2:3]
	s_cbranch_vccnz .LBB0_407
.LBB0_411:
	s_mov_b32 s10, 0x22000
	v_lshlrev_b32_e32 v2, 16, v216
	v_and_b32_e32 v3, 0xffff0000, v216
	v_lshlrev_b32_e32 v68, 16, v217
	v_and_b32_e32 v69, 0xffff0000, v217
	v_pk_add_f32 v[72:73], v[68:69], 0 op_sel_hi:[1, 0]
	v_lshlrev_b32_e32 v68, 16, v218
	v_and_b32_e32 v69, 0xffff0000, v218
	v_pk_add_f32 v[74:75], v[68:69], 0 op_sel_hi:[1, 0]
	v_lshlrev_b32_e32 v70, 16, v219
	v_and_b32_e32 v71, 0xffff0000, v219
	v_pk_add_f32 v[76:77], v[70:71], 0 op_sel_hi:[1, 0]
	s_mov_b32 s10, 0x42000
	v_pk_add_f32 v[2:3], v[2:3], 0 op_sel_hi:[1, 0]
	v_lshlrev_b32_e32 v78, 16, v220
	v_and_b32_e32 v79, 0xffff0000, v220
	v_lshlrev_b32_e32 v68, 16, v221
	v_and_b32_e32 v69, 0xffff0000, v221
	v_pk_add_f32 v[72:73], v[72:73], v[68:69]
	v_lshlrev_b32_e32 v68, 16, v222
	v_and_b32_e32 v69, 0xffff0000, v222
	v_pk_add_f32 v[74:75], v[74:75], v[68:69]
	v_lshlrev_b32_e32 v70, 16, v223
	v_and_b32_e32 v71, 0xffff0000, v223
	v_pk_add_f32 v[76:77], v[76:77], v[70:71]
	v_pk_add_f32 v[2:3], v[2:3], v[78:79]
	s_mov_b32 s10, 0x62000
	v_lshlrev_b32_e32 v78, 16, v224
	v_and_b32_e32 v79, 0xffff0000, v224
	v_lshlrev_b32_e32 v68, 16, v225
	v_and_b32_e32 v69, 0xffff0000, v225
	v_pk_add_f32 v[78:79], v[2:3], v[78:79]
	v_lshlrev_b32_e32 v2, 16, v226
	v_and_b32_e32 v3, 0xffff0000, v226
	v_lshlrev_b32_e32 v70, 16, v227
	v_and_b32_e32 v71, 0xffff0000, v227
	v_pk_add_f32 v[68:69], v[72:73], v[68:69]
	v_pk_add_f32 v[72:73], v[76:77], v[70:71]
	v_pk_add_f32 v[2:3], v[74:75], v[2:3]
	v_lshlrev_b32_e32 v80, 16, v228
	v_and_b32_e32 v81, 0xffff0000, v228
	v_lshlrev_b32_e32 v70, 16, v229
	v_and_b32_e32 v71, 0xffff0000, v229
	v_pk_add_f32 v[70:71], v[68:69], v[70:71]
	v_pk_add_f32 v[68:69], v[78:79], v[80:81]
	v_lshlrev_b32_e32 v78, 16, v230
	v_and_b32_e32 v79, 0xffff0000, v230
	v_lshlrev_b32_e32 v74, 16, v231
	v_and_b32_e32 v75, 0xffff0000, v231
	v_pk_add_f32 v[74:75], v[72:73], v[74:75]
	v_pk_add_f32 v[72:73], v[2:3], v[78:79]
	s_and_b64 vcc, exec, s[2:3]
	s_cbranch_vccnz .LBB0_408
.LBB0_412:
	s_mov_b32 s10, 0x22000
	v_lshlrev_b32_e32 v2, 16, v232
	v_and_b32_e32 v3, 0xffff0000, v232
	v_lshlrev_b32_e32 v76, 16, v233
	v_and_b32_e32 v77, 0xffff0000, v233
	v_pk_add_f32 v[80:81], v[76:77], 0 op_sel_hi:[1, 0]
	v_lshlrev_b32_e32 v76, 16, v234
	v_and_b32_e32 v77, 0xffff0000, v234
	v_pk_add_f32 v[82:83], v[76:77], 0 op_sel_hi:[1, 0]
	v_lshlrev_b32_e32 v78, 16, v235
	v_and_b32_e32 v79, 0xffff0000, v235
	v_pk_add_f32 v[84:85], v[78:79], 0 op_sel_hi:[1, 0]
	s_mov_b32 s10, 0x42000
	v_pk_add_f32 v[2:3], v[2:3], 0 op_sel_hi:[1, 0]
	v_lshlrev_b32_e32 v86, 16, v236
	v_and_b32_e32 v87, 0xffff0000, v236
	v_lshlrev_b32_e32 v76, 16, v237
	v_and_b32_e32 v77, 0xffff0000, v237
	v_pk_add_f32 v[80:81], v[80:81], v[76:77]
	v_lshlrev_b32_e32 v76, 16, v238
	v_and_b32_e32 v77, 0xffff0000, v238
	v_pk_add_f32 v[82:83], v[82:83], v[76:77]
	v_lshlrev_b32_e32 v78, 16, v239
	v_and_b32_e32 v79, 0xffff0000, v239
	v_pk_add_f32 v[84:85], v[84:85], v[78:79]
	v_pk_add_f32 v[2:3], v[2:3], v[86:87]
	s_mov_b32 s10, 0x62000
	v_lshlrev_b32_e32 v86, 16, v240
	v_and_b32_e32 v87, 0xffff0000, v240
	v_lshlrev_b32_e32 v76, 16, v241
	v_and_b32_e32 v77, 0xffff0000, v241
	v_pk_add_f32 v[86:87], v[2:3], v[86:87]
	v_lshlrev_b32_e32 v2, 16, v242
	v_and_b32_e32 v3, 0xffff0000, v242
	v_lshlrev_b32_e32 v78, 16, v243
	v_and_b32_e32 v79, 0xffff0000, v243
	v_pk_add_f32 v[76:77], v[80:81], v[76:77]
	v_pk_add_f32 v[80:81], v[84:85], v[78:79]
	v_pk_add_f32 v[2:3], v[82:83], v[2:3]
	v_lshlrev_b32_e32 v88, 16, v244
	v_and_b32_e32 v89, 0xffff0000, v244
	v_lshlrev_b32_e32 v78, 16, v245
	v_and_b32_e32 v79, 0xffff0000, v245
	v_pk_add_f32 v[78:79], v[76:77], v[78:79]
	v_pk_add_f32 v[76:77], v[86:87], v[88:89]
	v_lshlrev_b32_e32 v86, 16, v246
	v_and_b32_e32 v87, 0xffff0000, v246
	v_lshlrev_b32_e32 v82, 16, v247
	v_and_b32_e32 v83, 0xffff0000, v247
	v_pk_add_f32 v[82:83], v[80:81], v[82:83]
	v_pk_add_f32 v[80:81], v[2:3], v[86:87]
.LBB0_413:
	v_readlane_b32 s12, v255, 9
	v_readlane_b32 s13, v255, 10
	s_andn2_b64 vcc, exec, s[12:13]
	s_nop 0
	v_cndmask_b32_e64 v1, 0, 1, s[12:13]
	v_cmp_ne_u32_e64 s[10:11], 1, v1
	s_cbranch_vccnz .LBB0_416
	s_mov_b32 s12, 0x22000
	v_lshlrev_b32_e32 v2, 16, v216
	v_and_b32_e32 v3, 0xffff0000, v216
	v_lshlrev_b32_e32 v84, 16, v217
	v_and_b32_e32 v85, 0xffff0000, v217
	v_pk_add_f32 v[88:89], v[84:85], 0 op_sel_hi:[1, 0]
	v_lshlrev_b32_e32 v84, 16, v218
	v_and_b32_e32 v85, 0xffff0000, v218
	v_pk_add_f32 v[90:91], v[84:85], 0 op_sel_hi:[1, 0]
	v_lshlrev_b32_e32 v86, 16, v219
	v_and_b32_e32 v87, 0xffff0000, v219
	v_pk_add_f32 v[92:93], v[86:87], 0 op_sel_hi:[1, 0]
	s_mov_b32 s12, 0x42000
	v_pk_add_f32 v[2:3], v[2:3], 0 op_sel_hi:[1, 0]
	v_lshlrev_b32_e32 v94, 16, v220
	v_and_b32_e32 v95, 0xffff0000, v220
	v_lshlrev_b32_e32 v84, 16, v221
	v_and_b32_e32 v85, 0xffff0000, v221
	v_pk_add_f32 v[88:89], v[88:89], v[84:85]
	v_lshlrev_b32_e32 v84, 16, v222
	v_and_b32_e32 v85, 0xffff0000, v222
	v_pk_add_f32 v[90:91], v[90:91], v[84:85]
	v_lshlrev_b32_e32 v86, 16, v223
	v_and_b32_e32 v87, 0xffff0000, v223
	v_pk_add_f32 v[92:93], v[92:93], v[86:87]
	v_pk_add_f32 v[2:3], v[2:3], v[94:95]
	s_mov_b32 s12, 0x62000
	v_lshlrev_b32_e32 v94, 16, v224
	v_and_b32_e32 v95, 0xffff0000, v224
	v_lshlrev_b32_e32 v84, 16, v225
	v_and_b32_e32 v85, 0xffff0000, v225
	v_pk_add_f32 v[94:95], v[2:3], v[94:95]
	v_lshlrev_b32_e32 v2, 16, v226
	v_and_b32_e32 v3, 0xffff0000, v226
	v_lshlrev_b32_e32 v86, 16, v227
	v_and_b32_e32 v87, 0xffff0000, v227
	v_pk_add_f32 v[84:85], v[88:89], v[84:85]
	v_pk_add_f32 v[88:89], v[92:93], v[86:87]
	v_pk_add_f32 v[2:3], v[90:91], v[2:3]
	v_lshlrev_b32_e32 v96, 16, v228
	v_and_b32_e32 v97, 0xffff0000, v228
	v_lshlrev_b32_e32 v86, 16, v229
	v_and_b32_e32 v87, 0xffff0000, v229
	v_pk_add_f32 v[86:87], v[84:85], v[86:87]
	v_pk_add_f32 v[84:85], v[94:95], v[96:97]
	v_lshlrev_b32_e32 v94, 16, v230
	v_and_b32_e32 v95, 0xffff0000, v230
	v_lshlrev_b32_e32 v90, 16, v231
	v_and_b32_e32 v91, 0xffff0000, v231
	v_pk_add_f32 v[90:91], v[88:89], v[90:91]
	v_pk_add_f32 v[88:89], v[2:3], v[94:95]
	s_and_b64 vcc, exec, s[10:11]
	s_cbranch_vccz .LBB0_417

.LBB0_417:
	s_mov_b32 s12, 0x22000
	v_lshlrev_b32_e32 v2, 16, v232
	v_and_b32_e32 v3, 0xffff0000, v232
	v_lshlrev_b32_e32 v92, 16, v233
	v_and_b32_e32 v93, 0xffff0000, v233
	v_pk_add_f32 v[96:97], v[92:93], 0 op_sel_hi:[1, 0]
	v_lshlrev_b32_e32 v92, 16, v234
	v_and_b32_e32 v93, 0xffff0000, v234
	v_pk_add_f32 v[98:99], v[92:93], 0 op_sel_hi:[1, 0]
	v_lshlrev_b32_e32 v94, 16, v235
	v_and_b32_e32 v95, 0xffff0000, v235
	v_pk_add_f32 v[100:101], v[94:95], 0 op_sel_hi:[1, 0]
	s_mov_b32 s12, 0x42000
	v_pk_add_f32 v[2:3], v[2:3], 0 op_sel_hi:[1, 0]
	v_lshlrev_b32_e32 v102, 16, v236
	v_and_b32_e32 v103, 0xffff0000, v236
	v_lshlrev_b32_e32 v92, 16, v237
	v_and_b32_e32 v93, 0xffff0000, v237
	v_pk_add_f32 v[96:97], v[96:97], v[92:93]
	v_lshlrev_b32_e32 v92, 16, v238
	v_and_b32_e32 v93, 0xffff0000, v238
	v_pk_add_f32 v[98:99], v[98:99], v[92:93]
	v_lshlrev_b32_e32 v94, 16, v239
	v_and_b32_e32 v95, 0xffff0000, v239
	v_pk_add_f32 v[100:101], v[100:101], v[94:95]
	v_pk_add_f32 v[2:3], v[2:3], v[102:103]
	s_mov_b32 s12, 0x62000
	v_lshlrev_b32_e32 v102, 16, v240
	v_and_b32_e32 v103, 0xffff0000, v240
	v_lshlrev_b32_e32 v92, 16, v241
	v_and_b32_e32 v93, 0xffff0000, v241
	v_pk_add_f32 v[102:103], v[2:3], v[102:103]
	v_lshlrev_b32_e32 v2, 16, v242
	v_and_b32_e32 v3, 0xffff0000, v242
	v_lshlrev_b32_e32 v94, 16, v243
	v_and_b32_e32 v95, 0xffff0000, v243
	v_pk_add_f32 v[92:93], v[96:97], v[92:93]
	v_pk_add_f32 v[96:97], v[100:101], v[94:95]
	v_pk_add_f32 v[2:3], v[98:99], v[2:3]
	v_lshlrev_b32_e32 v104, 16, v244
	v_and_b32_e32 v105, 0xffff0000, v244
	v_lshlrev_b32_e32 v94, 16, v245
	v_and_b32_e32 v95, 0xffff0000, v245
	v_pk_add_f32 v[94:95], v[92:93], v[94:95]
	v_pk_add_f32 v[92:93], v[102:103], v[104:105]
	v_lshlrev_b32_e32 v102, 16, v246
	v_and_b32_e32 v103, 0xffff0000, v246
	v_lshlrev_b32_e32 v98, 16, v247
	v_and_b32_e32 v99, 0xffff0000, v247
	v_pk_add_f32 v[98:99], v[96:97], v[98:99]
	v_pk_add_f32 v[96:97], v[2:3], v[102:103]
.LBB0_418:
	v_readlane_b32 s14, v255, 11
	v_readlane_b32 s15, v255, 12
	s_andn2_b64 vcc, exec, s[14:15]
	s_nop 0
	v_cndmask_b32_e64 v1, 0, 1, s[14:15]
	v_cmp_ne_u32_e64 s[12:13], 1, v1
	s_cbranch_vccnz .LBB0_423
	v_lshlrev_b32_e32 v2, 16, v216
	v_and_b32_e32 v3, 0xffff0000, v216
	v_lshlrev_b32_e32 v100, 16, v217
	v_and_b32_e32 v101, 0xffff0000, v217
	v_pk_add_f32 v[104:105], v[100:101], 0 op_sel_hi:[1, 0]
	v_lshlrev_b32_e32 v100, 16, v218
	v_and_b32_e32 v101, 0xffff0000, v218
	v_pk_add_f32 v[106:107], v[100:101], 0 op_sel_hi:[1, 0]
	v_lshlrev_b32_e32 v102, 16, v219
	v_and_b32_e32 v103, 0xffff0000, v219
	v_pk_add_f32 v[108:109], v[102:103], 0 op_sel_hi:[1, 0]
	v_pk_add_f32 v[2:3], v[2:3], 0 op_sel_hi:[1, 0]
	v_lshlrev_b32_e32 v110, 16, v220
	v_and_b32_e32 v111, 0xffff0000, v220
	v_lshlrev_b32_e32 v100, 16, v221
	v_and_b32_e32 v101, 0xffff0000, v221
	v_pk_add_f32 v[104:105], v[104:105], v[100:101]
	v_lshlrev_b32_e32 v100, 16, v222
	v_and_b32_e32 v101, 0xffff0000, v222
	v_pk_add_f32 v[106:107], v[106:107], v[100:101]
	v_lshlrev_b32_e32 v102, 16, v223
	v_and_b32_e32 v103, 0xffff0000, v223
	v_pk_add_f32 v[108:109], v[108:109], v[102:103]
	v_pk_add_f32 v[2:3], v[2:3], v[110:111]
	v_lshlrev_b32_e32 v110, 16, v224
	v_and_b32_e32 v111, 0xffff0000, v224
	v_lshlrev_b32_e32 v100, 16, v225
	v_and_b32_e32 v101, 0xffff0000, v225
	v_pk_add_f32 v[110:111], v[2:3], v[110:111]
	v_lshlrev_b32_e32 v2, 16, v226
	v_and_b32_e32 v3, 0xffff0000, v226
	v_lshlrev_b32_e32 v102, 16, v227
	v_and_b32_e32 v103, 0xffff0000, v227
	v_pk_add_f32 v[100:101], v[104:105], v[100:101]
	v_pk_add_f32 v[104:105], v[108:109], v[102:103]
	v_pk_add_f32 v[2:3], v[106:107], v[2:3]
	v_lshlrev_b32_e32 v112, 16, v228
	v_and_b32_e32 v113, 0xffff0000, v228
	v_lshlrev_b32_e32 v102, 16, v229
	v_and_b32_e32 v103, 0xffff0000, v229
	v_pk_add_f32 v[102:103], v[100:101], v[102:103]
	v_pk_add_f32 v[100:101], v[110:111], v[112:113]
	v_lshlrev_b32_e32 v110, 16, v230
	v_and_b32_e32 v111, 0xffff0000, v230
	v_lshlrev_b32_e32 v106, 16, v231
	v_and_b32_e32 v107, 0xffff0000, v231
	v_pk_add_f32 v[106:107], v[104:105], v[106:107]
	v_pk_add_f32 v[104:105], v[2:3], v[110:111]
	s_and_b64 vcc, exec, s[12:13]
	s_cbranch_vccz .LBB0_424

.LBB0_424:
	v_lshlrev_b32_e32 v2, 16, v232
	v_and_b32_e32 v3, 0xffff0000, v232
	v_lshlrev_b32_e32 v108, 16, v233
	v_and_b32_e32 v109, 0xffff0000, v233
	v_pk_add_f32 v[112:113], v[108:109], 0 op_sel_hi:[1, 0]
	v_lshlrev_b32_e32 v108, 16, v234
	v_and_b32_e32 v109, 0xffff0000, v234
	v_pk_add_f32 v[114:115], v[108:109], 0 op_sel_hi:[1, 0]
	v_lshlrev_b32_e32 v110, 16, v235
	v_and_b32_e32 v111, 0xffff0000, v235
	v_pk_add_f32 v[116:117], v[110:111], 0 op_sel_hi:[1, 0]
	v_pk_add_f32 v[2:3], v[2:3], 0 op_sel_hi:[1, 0]
	v_lshlrev_b32_e32 v118, 16, v236
	v_and_b32_e32 v119, 0xffff0000, v236
	v_lshlrev_b32_e32 v108, 16, v237
	v_and_b32_e32 v109, 0xffff0000, v237
	v_pk_add_f32 v[112:113], v[112:113], v[108:109]
	v_lshlrev_b32_e32 v108, 16, v238
	v_and_b32_e32 v109, 0xffff0000, v238
	v_pk_add_f32 v[114:115], v[114:115], v[108:109]
	v_lshlrev_b32_e32 v110, 16, v239
	v_and_b32_e32 v111, 0xffff0000, v239
	v_pk_add_f32 v[116:117], v[116:117], v[110:111]
	v_pk_add_f32 v[2:3], v[2:3], v[118:119]
	v_lshlrev_b32_e32 v118, 16, v240
	v_and_b32_e32 v119, 0xffff0000, v240
	v_lshlrev_b32_e32 v108, 16, v241
	v_and_b32_e32 v109, 0xffff0000, v241
	v_pk_add_f32 v[118:119], v[2:3], v[118:119]
	v_lshlrev_b32_e32 v2, 16, v242
	v_and_b32_e32 v3, 0xffff0000, v242
	v_lshlrev_b32_e32 v110, 16, v243
	v_and_b32_e32 v111, 0xffff0000, v243
	v_pk_add_f32 v[108:109], v[112:113], v[108:109]
	v_pk_add_f32 v[112:113], v[116:117], v[110:111]
	v_pk_add_f32 v[2:3], v[114:115], v[2:3]
	v_lshlrev_b32_e32 v120, 16, v244
	v_and_b32_e32 v121, 0xffff0000, v244
	v_lshlrev_b32_e32 v110, 16, v245
	v_and_b32_e32 v111, 0xffff0000, v245
	v_pk_add_f32 v[110:111], v[108:109], v[110:111]
	v_pk_add_f32 v[108:109], v[118:119], v[120:121]
	v_lshlrev_b32_e32 v118, 16, v246
	v_and_b32_e32 v119, 0xffff0000, v246
	v_lshlrev_b32_e32 v114, 16, v247
	v_and_b32_e32 v115, 0xffff0000, v247
	v_pk_add_f32 v[114:115], v[112:113], v[114:115]
	v_pk_add_f32 v[112:113], v[2:3], v[118:119]
	s_and_b64 vcc, exec, s[8:9]
	s_cbranch_vccnz .LBB0_421
.LBB0_425:
	v_lshlrev_b32_e32 v2, 16, v216
	v_and_b32_e32 v3, 0xffff0000, v216
	v_lshlrev_b32_e32 v116, 16, v217
	v_and_b32_e32 v117, 0xffff0000, v217
	v_pk_add_f32 v[120:121], v[116:117], 0 op_sel_hi:[1, 0]
	v_lshlrev_b32_e32 v116, 16, v218
	v_and_b32_e32 v117, 0xffff0000, v218
	v_pk_add_f32 v[122:123], v[116:117], 0 op_sel_hi:[1, 0]
	v_lshlrev_b32_e32 v118, 16, v219
	v_and_b32_e32 v119, 0xffff0000, v219
	v_pk_add_f32 v[126:127], v[118:119], 0 op_sel_hi:[1, 0]
	v_pk_add_f32 v[2:3], v[2:3], 0 op_sel_hi:[1, 0]
	v_lshlrev_b32_e32 v128, 16, v220
	v_and_b32_e32 v129, 0xffff0000, v220
	v_lshlrev_b32_e32 v116, 16, v221
	v_and_b32_e32 v117, 0xffff0000, v221
	v_pk_add_f32 v[120:121], v[120:121], v[116:117]
	v_lshlrev_b32_e32 v116, 16, v222
	v_and_b32_e32 v117, 0xffff0000, v222
	v_pk_add_f32 v[122:123], v[122:123], v[116:117]
	v_lshlrev_b32_e32 v118, 16, v223
	v_and_b32_e32 v119, 0xffff0000, v223
	v_pk_add_f32 v[126:127], v[126:127], v[118:119]
	v_pk_add_f32 v[2:3], v[2:3], v[128:129]
	v_lshlrev_b32_e32 v128, 16, v224
	v_and_b32_e32 v129, 0xffff0000, v224
	v_lshlrev_b32_e32 v116, 16, v225
	v_and_b32_e32 v117, 0xffff0000, v225
	v_pk_add_f32 v[130:131], v[2:3], v[128:129]
	v_lshlrev_b32_e32 v2, 16, v226
	v_and_b32_e32 v3, 0xffff0000, v226
	v_lshlrev_b32_e32 v118, 16, v227
	v_and_b32_e32 v119, 0xffff0000, v227
	v_pk_add_f32 v[116:117], v[120:121], v[116:117]
	v_pk_add_f32 v[120:121], v[126:127], v[118:119]
	v_pk_add_f32 v[2:3], v[122:123], v[2:3]
	v_lshlrev_b32_e32 v122, 16, v228
	v_and_b32_e32 v123, 0xffff0000, v228
	v_lshlrev_b32_e32 v118, 16, v229
	v_and_b32_e32 v119, 0xffff0000, v229
	v_pk_add_f32 v[118:119], v[116:117], v[118:119]
	v_pk_add_f32 v[116:117], v[130:131], v[122:123]
	v_lshlrev_b32_e32 v126, 16, v230
	v_and_b32_e32 v127, 0xffff0000, v230
	v_lshlrev_b32_e32 v122, 16, v231
	v_and_b32_e32 v123, 0xffff0000, v231
	v_pk_add_f32 v[122:123], v[120:121], v[122:123]
	v_pk_add_f32 v[120:121], v[2:3], v[126:127]
	s_and_b64 vcc, exec, s[8:9]
	s_cbranch_vccnz .LBB0_422
.LBB0_426:
	v_lshlrev_b32_e32 v2, 16, v232
	v_and_b32_e32 v3, 0xffff0000, v232
	v_lshlrev_b32_e32 v126, 16, v233
	v_and_b32_e32 v127, 0xffff0000, v233
	v_pk_add_f32 v[130:131], v[126:127], 0 op_sel_hi:[1, 0]
	v_lshlrev_b32_e32 v126, 16, v234
	v_and_b32_e32 v127, 0xffff0000, v234
	v_pk_add_f32 v[132:133], v[126:127], 0 op_sel_hi:[1, 0]
	v_lshlrev_b32_e32 v128, 16, v235
	v_and_b32_e32 v129, 0xffff0000, v235
	v_pk_add_f32 v[134:135], v[128:129], 0 op_sel_hi:[1, 0]
	v_pk_add_f32 v[2:3], v[2:3], 0 op_sel_hi:[1, 0]
	v_lshlrev_b32_e32 v136, 16, v236
	v_and_b32_e32 v137, 0xffff0000, v236
	v_lshlrev_b32_e32 v126, 16, v237
	v_and_b32_e32 v127, 0xffff0000, v237
	v_pk_add_f32 v[130:131], v[130:131], v[126:127]
	v_lshlrev_b32_e32 v126, 16, v238
	v_and_b32_e32 v127, 0xffff0000, v238
	v_pk_add_f32 v[132:133], v[132:133], v[126:127]
	v_lshlrev_b32_e32 v128, 16, v239
	v_and_b32_e32 v129, 0xffff0000, v239
	v_pk_add_f32 v[134:135], v[134:135], v[128:129]
	v_pk_add_f32 v[2:3], v[2:3], v[136:137]
	v_lshlrev_b32_e32 v136, 16, v240
	v_and_b32_e32 v137, 0xffff0000, v240
	v_lshlrev_b32_e32 v126, 16, v241
	v_and_b32_e32 v127, 0xffff0000, v241
	v_pk_add_f32 v[136:137], v[2:3], v[136:137]
	v_lshlrev_b32_e32 v2, 16, v242
	v_and_b32_e32 v3, 0xffff0000, v242
	v_pk_add_f32 v[126:127], v[130:131], v[126:127]
	v_pk_add_f32 v[2:3], v[132:133], v[2:3]
	v_lshlrev_b32_e32 v128, 16, v243
	v_and_b32_e32 v129, 0xffff0000, v243
	v_pk_add_f32 v[128:129], v[134:135], v[128:129]
	v_lshlrev_b32_e32 v124, 16, v244
	v_and_b32_e32 v125, 0xffff0000, v244
	v_lshlrev_b32_e32 v130, 16, v245
	v_and_b32_e32 v131, 0xffff0000, v245
	v_pk_add_f32 v[126:127], v[126:127], v[130:131]
	v_lshlrev_b32_e32 v134, 16, v246
	v_and_b32_e32 v135, 0xffff0000, v246
	v_lshlrev_b32_e32 v130, 16, v247
	v_and_b32_e32 v131, 0xffff0000, v247
	v_pk_add_f32 v[124:125], v[136:137], v[124:125]
	v_pk_add_f32 v[130:131], v[128:129], v[130:131]
	v_pk_add_f32 v[128:129], v[2:3], v[134:135]

.LBB0_2319:
	s_lshl_b32 s4, s10, 1
	s_ashr_i32 s5, s4, 31
	s_sub_i32 s18, s91, s4
	s_lshl_b64 s[4:5], s[4:5], 17
	v_readlane_b32 s8, v254, 63
	v_readlane_b32 s9, v255, 0
	s_add_u32 s4, s8, s4
	s_addc_u32 s5, s9, s5
	v_add_u32_e32 v0, s97, v128
	v_ashrrev_i32_e32 v1, 31, v0
	s_cmp_eq_u32 s18, 0
	v_lshl_add_u64 v[12:13], v[0:1], 4, s[4:5]
	s_cselect_b64 s[4:5], -1, 0
	v_mov_b32_e32 v0, 0
	s_and_b64 vcc, exec, s[4:5]
	v_mov_b32_e32 v2, 0
	v_mov_b32_e32 v3, 0
	v_mov_b32_e32 v6, 0
	v_mov_b32_e32 v7, 0
	v_mov_b32_e32 v4, 0
	v_mov_b32_e32 v5, 0
	v_mov_b32_e32 v8, 0
	v_mov_b32_e32 v9, 0
	s_waitcnt vmcnt(0)
	s_barrier
	v_readlane_b32 s100, v255, 33
	s_nop 3
	s_and_b32 s100, s100, 1
	s_lshl_b32 s100, s100, 11
	s_mov_b32 s101, 0
	v_lshl_add_u64 v[228:229], s[100:101], 0, v[12:13]
	global_load_dwordx4 v[164:167], v[228:229], off
	global_load_dwordx4 v[172:175], v[228:229], off offset:1024
	s_mov_b32 s100, 0x20000
	v_lshl_add_u64 v[230:231], s[100:101], 0, v[228:229]
	global_load_dwordx4 v[168:171], v[230:231], off
	global_load_dwordx4 v[176:179], v[230:231], off offset:1024
	s_mov_b32 s100, 0x1000
	v_lshl_add_u64 v[230:231], s[100:101], 0, v[228:229]
	global_load_dwordx4 v[180:183], v[230:231], off
	global_load_dwordx4 v[188:191], v[230:231], off offset:1024
	s_mov_b32 s100, 0x21000
	v_lshl_add_u64 v[230:231], s[100:101], 0, v[228:229]
	global_load_dwordx4 v[184:187], v[230:231], off
	global_load_dwordx4 v[192:195], v[230:231], off offset:1024
	s_mov_b32 s100, 0x2000
	v_lshl_add_u64 v[230:231], s[100:101], 0, v[228:229]
	global_load_dwordx4 v[196:199], v[230:231], off
	global_load_dwordx4 v[204:207], v[230:231], off offset:1024
	s_mov_b32 s100, 0x22000
	v_lshl_add_u64 v[230:231], s[100:101], 0, v[228:229]
	global_load_dwordx4 v[200:203], v[230:231], off
	global_load_dwordx4 v[208:211], v[230:231], off offset:1024
	s_mov_b32 s100, 0x3000
	v_lshl_add_u64 v[230:231], s[100:101], 0, v[228:229]
	global_load_dwordx4 v[212:215], v[230:231], off
	global_load_dwordx4 v[220:223], v[230:231], off offset:1024
	s_mov_b32 s100, 0x23000
	v_lshl_add_u64 v[230:231], s[100:101], 0, v[228:229]
	global_load_dwordx4 v[216:219], v[230:231], off
	global_load_dwordx4 v[224:227], v[230:231], off offset:1024
	s_waitcnt vmcnt(0)
	s_cbranch_vccz .LBB0_2321
	s_mov_b32 s8, 0x20000
	v_lshlrev_b32_e32 v10, 16, v164
	v_and_b32_e32 v11, 0xffff0000, v164
	v_lshlrev_b32_e32 v2, 16, v165
	v_and_b32_e32 v3, 0xffff0000, v165
	v_lshlrev_b32_e32 v14, 16, v166
	v_and_b32_e32 v15, 0xffff0000, v166
	v_lshlrev_b32_e32 v4, 16, v167
	v_and_b32_e32 v5, 0xffff0000, v167
	v_pk_add_f32 v[10:11], v[10:11], 0 op_sel_hi:[1, 0]
	v_pk_add_f32 v[2:3], v[2:3], 0 op_sel_hi:[1, 0]
	v_pk_add_f32 v[14:15], v[14:15], 0 op_sel_hi:[1, 0]
	v_pk_add_f32 v[4:5], v[4:5], 0 op_sel_hi:[1, 0]
	v_lshlrev_b32_e32 v16, 16, v168
	v_and_b32_e32 v17, 0xffff0000, v168
	v_lshlrev_b32_e32 v6, 16, v169
	v_and_b32_e32 v7, 0xffff0000, v169
	v_lshlrev_b32_e32 v18, 16, v170
	v_and_b32_e32 v19, 0xffff0000, v170
	v_lshlrev_b32_e32 v8, 16, v171
	v_and_b32_e32 v9, 0xffff0000, v171
	v_pk_add_f32 v[6:7], v[2:3], v[6:7]
	v_pk_add_f32 v[2:3], v[10:11], v[16:17]
	v_pk_add_f32 v[8:9], v[4:5], v[8:9]
	v_pk_add_f32 v[4:5], v[14:15], v[18:19]
.LBB0_2321:
	v_cndmask_b32_e64 v1, 0, 1, s[4:5]
	v_cmp_ne_u32_e64 s[8:9], 1, v1
	s_andn2_b64 vcc, exec, s[4:5]
	v_mov_b32_e32 v1, 0
	v_mov_b32_e32 v16, 0
	v_mov_b32_e32 v17, 0
	v_mov_b32_e32 v14, 0
	v_mov_b32_e32 v15, 0
	v_mov_b32_e32 v18, 0
	v_mov_b32_e32 v19, 0
	s_cbranch_vccnz .LBB0_2323
	s_mov_b32 s10, 0x20000
	v_lshlrev_b32_e32 v0, 16, v172
	v_and_b32_e32 v1, 0xffff0000, v172
	v_lshlrev_b32_e32 v10, 16, v173
	v_and_b32_e32 v11, 0xffff0000, v173
	v_lshlrev_b32_e32 v14, 16, v174
	v_and_b32_e32 v15, 0xffff0000, v174
	v_lshlrev_b32_e32 v16, 16, v175
	v_and_b32_e32 v17, 0xffff0000, v175
	v_pk_add_f32 v[0:1], v[0:1], 0 op_sel_hi:[1, 0]
	v_pk_add_f32 v[10:11], v[10:11], 0 op_sel_hi:[1, 0]
	v_pk_add_f32 v[14:15], v[14:15], 0 op_sel_hi:[1, 0]
	v_pk_add_f32 v[22:23], v[16:17], 0 op_sel_hi:[1, 0]
	v_lshlrev_b32_e32 v24, 16, v176
	v_and_b32_e32 v25, 0xffff0000, v176
	v_lshlrev_b32_e32 v16, 16, v177
	v_and_b32_e32 v17, 0xffff0000, v177
	v_lshlrev_b32_e32 v26, 16, v178
	v_and_b32_e32 v27, 0xffff0000, v178
	v_lshlrev_b32_e32 v18, 16, v179
	v_and_b32_e32 v19, 0xffff0000, v179
	v_pk_add_f32 v[16:17], v[10:11], v[16:17]
	v_pk_add_f32 v[0:1], v[0:1], v[24:25]
	v_pk_add_f32 v[18:19], v[22:23], v[18:19]
	v_pk_add_f32 v[14:15], v[14:15], v[26:27]
.LBB0_2323:
	s_add_i32 s14, s14, -1
	s_cmp_eq_u32 s14, s18
	v_mov_b32_e32 v10, 0
	s_cselect_b64 s[12:13], -1, 0
	s_cmp_lg_u32 s14, s18
	v_mov_b32_e32 v20, 0
	v_mov_b32_e32 v21, 0
	v_mov_b32_e32 v24, 0
	v_mov_b32_e32 v25, 0
	v_mov_b32_e32 v22, 0
	v_mov_b32_e32 v23, 0
	v_mov_b32_e32 v26, 0
	v_mov_b32_e32 v27, 0
	s_cbranch_scc1 .LBB0_2325
	s_mov_b32 s10, 0x20000
	v_lshlrev_b32_e32 v28, 16, v164
	v_and_b32_e32 v29, 0xffff0000, v164
	v_lshlrev_b32_e32 v20, 16, v165
	v_and_b32_e32 v21, 0xffff0000, v165
	v_lshlrev_b32_e32 v30, 16, v166
	v_and_b32_e32 v31, 0xffff0000, v166
	v_lshlrev_b32_e32 v22, 16, v167
	v_and_b32_e32 v23, 0xffff0000, v167
	v_pk_add_f32 v[28:29], v[28:29], 0 op_sel_hi:[1, 0]
	v_pk_add_f32 v[20:21], v[20:21], 0 op_sel_hi:[1, 0]
	v_pk_add_f32 v[30:31], v[30:31], 0 op_sel_hi:[1, 0]
	v_pk_add_f32 v[22:23], v[22:23], 0 op_sel_hi:[1, 0]
	v_lshlrev_b32_e32 v32, 16, v168
	v_and_b32_e32 v33, 0xffff0000, v168
	v_lshlrev_b32_e32 v24, 16, v169
	v_and_b32_e32 v25, 0xffff0000, v169
	v_lshlrev_b32_e32 v34, 16, v170
	v_and_b32_e32 v35, 0xffff0000, v170
	v_lshlrev_b32_e32 v26, 16, v171
	v_and_b32_e32 v27, 0xffff0000, v171
	v_pk_add_f32 v[24:25], v[20:21], v[24:25]
	v_pk_add_f32 v[20:21], v[28:29], v[32:33]
	v_pk_add_f32 v[26:27], v[22:23], v[26:27]
	v_pk_add_f32 v[22:23], v[30:31], v[34:35]
.LBB0_2325:
	v_cndmask_b32_e64 v11, 0, 1, s[12:13]
	v_cmp_ne_u32_e64 s[10:11], 1, v11
	s_andn2_b64 vcc, exec, s[12:13]
	v_mov_b32_e32 v11, 0
	v_mov_b32_e32 v32, 0
	v_mov_b32_e32 v33, 0
	v_mov_b32_e32 v30, 0
	v_mov_b32_e32 v31, 0
	v_mov_b32_e32 v34, 0
	v_mov_b32_e32 v35, 0
	s_cbranch_vccnz .LBB0_2327
	s_mov_b32 s12, 0x20000
	v_lshlrev_b32_e32 v10, 16, v172
	v_and_b32_e32 v11, 0xffff0000, v172
	v_lshlrev_b32_e32 v28, 16, v173
	v_and_b32_e32 v29, 0xffff0000, v173
	v_lshlrev_b32_e32 v36, 16, v174
	v_and_b32_e32 v37, 0xffff0000, v174
	v_lshlrev_b32_e32 v30, 16, v175
	v_and_b32_e32 v31, 0xffff0000, v175
	v_pk_add_f32 v[10:11], v[10:11], 0 op_sel_hi:[1, 0]
	v_pk_add_f32 v[28:29], v[28:29], 0 op_sel_hi:[1, 0]
	v_pk_add_f32 v[36:37], v[36:37], 0 op_sel_hi:[1, 0]
	v_pk_add_f32 v[30:31], v[30:31], 0 op_sel_hi:[1, 0]
	v_lshlrev_b32_e32 v38, 16, v176
	v_and_b32_e32 v39, 0xffff0000, v176
	v_lshlrev_b32_e32 v32, 16, v177
	v_and_b32_e32 v33, 0xffff0000, v177
	v_lshlrev_b32_e32 v40, 16, v178
	v_and_b32_e32 v41, 0xffff0000, v178
	v_lshlrev_b32_e32 v34, 16, v179
	v_and_b32_e32 v35, 0xffff0000, v179
	v_pk_add_f32 v[32:33], v[28:29], v[32:33]
	v_pk_add_f32 v[10:11], v[10:11], v[38:39]
	v_pk_add_f32 v[34:35], v[30:31], v[34:35]
	v_pk_add_f32 v[30:31], v[36:37], v[40:41]
.LBB0_2327:
	v_mov_b32_e32 v28, 0
	s_and_b64 vcc, exec, s[8:9]
	v_mov_b32_e32 v36, 0
	v_mov_b32_e32 v37, 0
	v_mov_b32_e32 v40, 0
	v_mov_b32_e32 v41, 0
	v_mov_b32_e32 v38, 0
	v_mov_b32_e32 v39, 0
	v_mov_b32_e32 v42, 0
	v_mov_b32_e32 v43, 0
	s_cbranch_vccnz .LBB0_2329
	s_mov_b32 s12, 0x21000
	v_lshlrev_b32_e32 v44, 16, v180
	v_and_b32_e32 v45, 0xffff0000, v180
	v_lshlrev_b32_e32 v36, 16, v181
	v_and_b32_e32 v37, 0xffff0000, v181
	v_lshlrev_b32_e32 v46, 16, v182
	v_and_b32_e32 v47, 0xffff0000, v182
	v_lshlrev_b32_e32 v38, 16, v183
	v_and_b32_e32 v39, 0xffff0000, v183
	v_lshlrev_b32_e32 v48, 16, v184
	v_and_b32_e32 v49, 0xffff0000, v184
	v_lshlrev_b32_e32 v40, 16, v185
	v_and_b32_e32 v41, 0xffff0000, v185
	v_lshlrev_b32_e32 v50, 16, v186
	v_and_b32_e32 v51, 0xffff0000, v186
	v_lshlrev_b32_e32 v42, 16, v187
	v_and_b32_e32 v43, 0xffff0000, v187
	v_pk_add_f32 v[44:45], v[44:45], 0 op_sel_hi:[1, 0]
	v_pk_add_f32 v[36:37], v[36:37], 0 op_sel_hi:[1, 0]
	v_pk_add_f32 v[46:47], v[46:47], 0 op_sel_hi:[1, 0]
	v_pk_add_f32 v[38:39], v[38:39], 0 op_sel_hi:[1, 0]
	v_pk_add_f32 v[40:41], v[36:37], v[40:41]
	v_pk_add_f32 v[36:37], v[44:45], v[48:49]
	v_pk_add_f32 v[42:43], v[38:39], v[42:43]
	v_pk_add_f32 v[38:39], v[46:47], v[50:51]
.LBB0_2329:
	s_and_b64 vcc, exec, s[8:9]
	v_mov_b32_e32 v29, 0
	v_mov_b32_e32 v48, 0
	v_mov_b32_e32 v49, 0
	v_mov_b32_e32 v46, 0
	v_mov_b32_e32 v47, 0
	v_mov_b32_e32 v50, 0
	v_mov_b32_e32 v51, 0
	s_cbranch_vccnz .LBB0_2331
	s_mov_b32 s12, 0x21000
	v_lshlrev_b32_e32 v52, 16, v190
	v_lshlrev_b32_e32 v28, 16, v188
	v_and_b32_e32 v29, 0xffff0000, v188
	v_lshlrev_b32_e32 v44, 16, v189
	v_and_b32_e32 v45, 0xffff0000, v189
	v_and_b32_e32 v53, 0xffff0000, v190
	v_lshlrev_b32_e32 v46, 16, v191
	v_and_b32_e32 v47, 0xffff0000, v191
	v_pk_add_f32 v[28:29], v[28:29], 0 op_sel_hi:[1, 0]
	v_pk_add_f32 v[44:45], v[44:45], 0 op_sel_hi:[1, 0]
	v_pk_add_f32 v[52:53], v[52:53], 0 op_sel_hi:[1, 0]
	v_pk_add_f32 v[46:47], v[46:47], 0 op_sel_hi:[1, 0]
	v_lshlrev_b32_e32 v54, 16, v192
	v_and_b32_e32 v55, 0xffff0000, v192
	v_lshlrev_b32_e32 v48, 16, v193
	v_and_b32_e32 v49, 0xffff0000, v193
	v_lshlrev_b32_e32 v56, 16, v194
	v_and_b32_e32 v57, 0xffff0000, v194
	v_lshlrev_b32_e32 v50, 16, v195
	v_and_b32_e32 v51, 0xffff0000, v195
	v_pk_add_f32 v[48:49], v[44:45], v[48:49]
	v_pk_add_f32 v[28:29], v[28:29], v[54:55]
	v_pk_add_f32 v[50:51], v[46:47], v[50:51]
	v_pk_add_f32 v[46:47], v[52:53], v[56:57]
.LBB0_2331:
	v_mov_b32_e32 v44, 0
	s_and_b64 vcc, exec, s[10:11]
	v_mov_b32_e32 v52, 0
	v_mov_b32_e32 v53, 0
	v_mov_b32_e32 v56, 0
	v_mov_b32_e32 v57, 0
	v_mov_b32_e32 v54, 0
	v_mov_b32_e32 v55, 0
	v_mov_b32_e32 v58, 0
	v_mov_b32_e32 v59, 0
	s_cbranch_vccnz .LBB0_2333
	s_mov_b32 s12, 0x21000
	v_lshlrev_b32_e32 v60, 16, v180
	v_and_b32_e32 v61, 0xffff0000, v180
	v_lshlrev_b32_e32 v52, 16, v181
	v_and_b32_e32 v53, 0xffff0000, v181
	v_lshlrev_b32_e32 v62, 16, v182
	v_and_b32_e32 v63, 0xffff0000, v182
	v_lshlrev_b32_e32 v54, 16, v183
	v_and_b32_e32 v55, 0xffff0000, v183
	v_lshlrev_b32_e32 v64, 16, v184
	v_and_b32_e32 v65, 0xffff0000, v184
	v_lshlrev_b32_e32 v56, 16, v185
	v_and_b32_e32 v57, 0xffff0000, v185
	v_lshlrev_b32_e32 v66, 16, v186
	v_and_b32_e32 v67, 0xffff0000, v186
	v_lshlrev_b32_e32 v58, 16, v187
	v_and_b32_e32 v59, 0xffff0000, v187
	v_pk_add_f32 v[60:61], v[60:61], 0 op_sel_hi:[1, 0]
	v_pk_add_f32 v[52:53], v[52:53], 0 op_sel_hi:[1, 0]
	v_pk_add_f32 v[62:63], v[62:63], 0 op_sel_hi:[1, 0]
	v_pk_add_f32 v[54:55], v[54:55], 0 op_sel_hi:[1, 0]
	v_pk_add_f32 v[56:57], v[52:53], v[56:57]
	v_pk_add_f32 v[52:53], v[60:61], v[64:65]
	v_pk_add_f32 v[58:59], v[54:55], v[58:59]
	v_pk_add_f32 v[54:55], v[62:63], v[66:67]
.LBB0_2333:
	s_and_b64 vcc, exec, s[10:11]
	v_mov_b32_e32 v45, 0
	v_mov_b32_e32 v64, 0
	v_mov_b32_e32 v65, 0
	v_mov_b32_e32 v62, 0
	v_mov_b32_e32 v63, 0
	v_mov_b32_e32 v66, 0
	v_mov_b32_e32 v67, 0
	s_cbranch_vccnz .LBB0_2335
	s_mov_b32 s12, 0x21000
	v_lshlrev_b32_e32 v68, 16, v190
	v_lshlrev_b32_e32 v44, 16, v188
	v_and_b32_e32 v45, 0xffff0000, v188
	v_lshlrev_b32_e32 v60, 16, v189
	v_and_b32_e32 v61, 0xffff0000, v189
	v_and_b32_e32 v69, 0xffff0000, v190
	v_lshlrev_b32_e32 v62, 16, v191
	v_and_b32_e32 v63, 0xffff0000, v191
	v_pk_add_f32 v[44:45], v[44:45], 0 op_sel_hi:[1, 0]
	v_pk_add_f32 v[60:61], v[60:61], 0 op_sel_hi:[1, 0]
	v_pk_add_f32 v[68:69], v[68:69], 0 op_sel_hi:[1, 0]
	v_pk_add_f32 v[62:63], v[62:63], 0 op_sel_hi:[1, 0]
	v_lshlrev_b32_e32 v70, 16, v192
	v_and_b32_e32 v71, 0xffff0000, v192
	v_lshlrev_b32_e32 v64, 16, v193
	v_and_b32_e32 v65, 0xffff0000, v193
	v_lshlrev_b32_e32 v72, 16, v194
	v_and_b32_e32 v73, 0xffff0000, v194
	v_lshlrev_b32_e32 v66, 16, v195
	v_and_b32_e32 v67, 0xffff0000, v195
	v_pk_add_f32 v[64:65], v[60:61], v[64:65]
	v_pk_add_f32 v[44:45], v[44:45], v[70:71]
	v_pk_add_f32 v[66:67], v[62:63], v[66:67]
	v_pk_add_f32 v[62:63], v[68:69], v[72:73]
.LBB0_2335:
	v_mov_b32_e32 v60, 0
	s_and_b64 vcc, exec, s[8:9]
	v_mov_b32_e32 v68, 0
	v_mov_b32_e32 v69, 0
	v_mov_b32_e32 v72, 0
	v_mov_b32_e32 v73, 0
	v_mov_b32_e32 v70, 0
	v_mov_b32_e32 v71, 0
	v_mov_b32_e32 v74, 0
	v_mov_b32_e32 v75, 0
	s_cbranch_vccnz .LBB0_2337
	s_mov_b32 s12, 0x22000
	v_lshlrev_b32_e32 v76, 16, v196
	v_and_b32_e32 v77, 0xffff0000, v196
	v_lshlrev_b32_e32 v68, 16, v197
	v_and_b32_e32 v69, 0xffff0000, v197
	v_lshlrev_b32_e32 v78, 16, v198
	v_and_b32_e32 v79, 0xffff0000, v198
	v_lshlrev_b32_e32 v70, 16, v199
	v_and_b32_e32 v71, 0xffff0000, v199
	v_lshlrev_b32_e32 v80, 16, v200
	v_and_b32_e32 v81, 0xffff0000, v200
	v_lshlrev_b32_e32 v72, 16, v201
	v_and_b32_e32 v73, 0xffff0000, v201
	v_lshlrev_b32_e32 v82, 16, v202
	v_and_b32_e32 v83, 0xffff0000, v202
	v_lshlrev_b32_e32 v74, 16, v203
	v_and_b32_e32 v75, 0xffff0000, v203
	v_pk_add_f32 v[76:77], v[76:77], 0 op_sel_hi:[1, 0]
	v_pk_add_f32 v[68:69], v[68:69], 0 op_sel_hi:[1, 0]
	v_pk_add_f32 v[78:79], v[78:79], 0 op_sel_hi:[1, 0]
	v_pk_add_f32 v[70:71], v[70:71], 0 op_sel_hi:[1, 0]
	v_pk_add_f32 v[72:73], v[68:69], v[72:73]
	v_pk_add_f32 v[68:69], v[76:77], v[80:81]
	v_pk_add_f32 v[74:75], v[70:71], v[74:75]
	v_pk_add_f32 v[70:71], v[78:79], v[82:83]
.LBB0_2337:
	s_and_b64 vcc, exec, s[8:9]
	v_mov_b32_e32 v61, 0
	v_mov_b32_e32 v80, 0
	v_mov_b32_e32 v81, 0
	v_mov_b32_e32 v78, 0
	v_mov_b32_e32 v79, 0
	v_mov_b32_e32 v82, 0
	v_mov_b32_e32 v83, 0
	s_cbranch_vccnz .LBB0_2339
	s_mov_b32 s12, 0x22000
	v_lshlrev_b32_e32 v84, 16, v206
	v_lshlrev_b32_e32 v60, 16, v204
	v_and_b32_e32 v61, 0xffff0000, v204
	v_lshlrev_b32_e32 v76, 16, v205
	v_and_b32_e32 v77, 0xffff0000, v205
	v_and_b32_e32 v85, 0xffff0000, v206
	v_lshlrev_b32_e32 v78, 16, v207
	v_and_b32_e32 v79, 0xffff0000, v207
	v_pk_add_f32 v[60:61], v[60:61], 0 op_sel_hi:[1, 0]
	v_pk_add_f32 v[76:77], v[76:77], 0 op_sel_hi:[1, 0]
	v_pk_add_f32 v[84:85], v[84:85], 0 op_sel_hi:[1, 0]
	v_pk_add_f32 v[78:79], v[78:79], 0 op_sel_hi:[1, 0]
	v_lshlrev_b32_e32 v86, 16, v208
	v_and_b32_e32 v87, 0xffff0000, v208
	v_lshlrev_b32_e32 v80, 16, v209
	v_and_b32_e32 v81, 0xffff0000, v209
	v_lshlrev_b32_e32 v88, 16, v210
	v_and_b32_e32 v89, 0xffff0000, v210
	v_lshlrev_b32_e32 v82, 16, v211
	v_and_b32_e32 v83, 0xffff0000, v211
	v_pk_add_f32 v[80:81], v[76:77], v[80:81]
	v_pk_add_f32 v[60:61], v[60:61], v[86:87]
	v_pk_add_f32 v[82:83], v[78:79], v[82:83]
	v_pk_add_f32 v[78:79], v[84:85], v[88:89]
.LBB0_2339:
	s_and_b32 s12, s14, 5
	s_cmp_eq_u32 s12, s18
	v_mov_b32_e32 v76, 0
	s_cselect_b64 s[14:15], -1, 0
	s_cmp_lg_u32 s12, s18
	v_mov_b32_e32 v84, 0
	v_mov_b32_e32 v85, 0
	v_mov_b32_e32 v88, 0
	v_mov_b32_e32 v89, 0
	v_mov_b32_e32 v86, 0
	v_mov_b32_e32 v87, 0
	v_mov_b32_e32 v90, 0
	v_mov_b32_e32 v91, 0
	s_cbranch_scc1 .LBB0_2341
	s_mov_b32 s12, 0x22000
	v_lshlrev_b32_e32 v92, 16, v196
	v_and_b32_e32 v93, 0xffff0000, v196
	v_lshlrev_b32_e32 v84, 16, v197
	v_and_b32_e32 v85, 0xffff0000, v197
	v_lshlrev_b32_e32 v94, 16, v198
	v_and_b32_e32 v95, 0xffff0000, v198
	v_lshlrev_b32_e32 v86, 16, v199
	v_and_b32_e32 v87, 0xffff0000, v199
	v_lshlrev_b32_e32 v96, 16, v200
	v_and_b32_e32 v97, 0xffff0000, v200
	v_lshlrev_b32_e32 v88, 16, v201
	v_and_b32_e32 v89, 0xffff0000, v201
	v_lshlrev_b32_e32 v98, 16, v202
	v_and_b32_e32 v99, 0xffff0000, v202
	v_lshlrev_b32_e32 v90, 16, v203
	v_and_b32_e32 v91, 0xffff0000, v203
	v_pk_add_f32 v[92:93], v[92:93], 0 op_sel_hi:[1, 0]
	v_pk_add_f32 v[84:85], v[84:85], 0 op_sel_hi:[1, 0]
	v_pk_add_f32 v[94:95], v[94:95], 0 op_sel_hi:[1, 0]
	v_pk_add_f32 v[86:87], v[86:87], 0 op_sel_hi:[1, 0]
	v_pk_add_f32 v[88:89], v[84:85], v[88:89]
	v_pk_add_f32 v[84:85], v[92:93], v[96:97]
	v_pk_add_f32 v[90:91], v[86:87], v[90:91]
	v_pk_add_f32 v[86:87], v[94:95], v[98:99]
.LBB0_2341:
	v_cndmask_b32_e64 v77, 0, 1, s[14:15]
	v_cmp_ne_u32_e64 s[12:13], 1, v77
	s_andn2_b64 vcc, exec, s[14:15]
	v_mov_b32_e32 v77, 0
	v_mov_b32_e32 v96, 0
	v_mov_b32_e32 v97, 0
	v_mov_b32_e32 v94, 0
	v_mov_b32_e32 v95, 0
	v_mov_b32_e32 v98, 0
	v_mov_b32_e32 v99, 0
	s_cbranch_vccnz .LBB0_2343
	s_mov_b32 s14, 0x22000
	v_lshlrev_b32_e32 v100, 16, v206
	v_lshlrev_b32_e32 v76, 16, v204
	v_and_b32_e32 v77, 0xffff0000, v204
	v_lshlrev_b32_e32 v92, 16, v205
	v_and_b32_e32 v93, 0xffff0000, v205
	v_and_b32_e32 v101, 0xffff0000, v206
	v_lshlrev_b32_e32 v94, 16, v207
	v_and_b32_e32 v95, 0xffff0000, v207
	v_pk_add_f32 v[76:77], v[76:77], 0 op_sel_hi:[1, 0]
	v_pk_add_f32 v[92:93], v[92:93], 0 op_sel_hi:[1, 0]
	v_pk_add_f32 v[100:101], v[100:101], 0 op_sel_hi:[1, 0]
	v_pk_add_f32 v[94:95], v[94:95], 0 op_sel_hi:[1, 0]
	v_lshlrev_b32_e32 v102, 16, v208
	v_and_b32_e32 v103, 0xffff0000, v208
	v_lshlrev_b32_e32 v96, 16, v209
	v_and_b32_e32 v97, 0xffff0000, v209
	v_lshlrev_b32_e32 v104, 16, v210
	v_and_b32_e32 v105, 0xffff0000, v210
	v_lshlrev_b32_e32 v98, 16, v211
	v_and_b32_e32 v99, 0xffff0000, v211
	v_pk_add_f32 v[96:97], v[92:93], v[96:97]
	v_pk_add_f32 v[76:77], v[76:77], v[102:103]
	v_pk_add_f32 v[98:99], v[94:95], v[98:99]
	v_pk_add_f32 v[94:95], v[100:101], v[104:105]
.LBB0_2343:
	v_mov_b32_e32 v92, 0
	s_and_b64 vcc, exec, s[8:9]
	v_mov_b32_e32 v100, 0
	v_mov_b32_e32 v101, 0
	v_mov_b32_e32 v104, 0
	v_mov_b32_e32 v105, 0
	v_mov_b32_e32 v102, 0
	v_mov_b32_e32 v103, 0
	v_mov_b32_e32 v106, 0
	v_mov_b32_e32 v107, 0
	s_cbranch_vccnz .LBB0_2345
	s_mov_b32 s14, 0x23000
	v_lshlrev_b32_e32 v108, 16, v212
	v_and_b32_e32 v109, 0xffff0000, v212
	v_lshlrev_b32_e32 v100, 16, v213
	v_and_b32_e32 v101, 0xffff0000, v213
	v_lshlrev_b32_e32 v110, 16, v214
	v_and_b32_e32 v111, 0xffff0000, v214
	v_lshlrev_b32_e32 v102, 16, v215
	v_and_b32_e32 v103, 0xffff0000, v215
	v_lshlrev_b32_e32 v112, 16, v216
	v_and_b32_e32 v113, 0xffff0000, v216
	v_lshlrev_b32_e32 v104, 16, v217
	v_and_b32_e32 v105, 0xffff0000, v217
	v_lshlrev_b32_e32 v114, 16, v218
	v_and_b32_e32 v115, 0xffff0000, v218
	v_lshlrev_b32_e32 v106, 16, v219
	v_and_b32_e32 v107, 0xffff0000, v219
	v_pk_add_f32 v[108:109], v[108:109], 0 op_sel_hi:[1, 0]
	v_pk_add_f32 v[100:101], v[100:101], 0 op_sel_hi:[1, 0]
	v_pk_add_f32 v[110:111], v[110:111], 0 op_sel_hi:[1, 0]
	v_pk_add_f32 v[102:103], v[102:103], 0 op_sel_hi:[1, 0]
	v_pk_add_f32 v[104:105], v[100:101], v[104:105]
	v_pk_add_f32 v[100:101], v[108:109], v[112:113]
	v_pk_add_f32 v[106:107], v[102:103], v[106:107]
	v_pk_add_f32 v[102:103], v[110:111], v[114:115]
.LBB0_2345:
	s_and_b64 vcc, exec, s[8:9]
	v_mov_b32_e32 v93, 0
	v_mov_b32_e32 v112, 0
	v_mov_b32_e32 v113, 0
	v_mov_b32_e32 v110, 0
	v_mov_b32_e32 v111, 0
	v_mov_b32_e32 v114, 0
	v_mov_b32_e32 v115, 0
	s_cbranch_vccnz .LBB0_2347
	s_mov_b32 s14, 0x23000
	v_lshlrev_b32_e32 v116, 16, v222
	v_lshlrev_b32_e32 v92, 16, v220
	v_and_b32_e32 v93, 0xffff0000, v220
	v_lshlrev_b32_e32 v108, 16, v221
	v_and_b32_e32 v109, 0xffff0000, v221
	v_and_b32_e32 v117, 0xffff0000, v222
	v_lshlrev_b32_e32 v110, 16, v223
	v_and_b32_e32 v111, 0xffff0000, v223
	v_pk_add_f32 v[92:93], v[92:93], 0 op_sel_hi:[1, 0]
	v_pk_add_f32 v[108:109], v[108:109], 0 op_sel_hi:[1, 0]
	v_pk_add_f32 v[116:117], v[116:117], 0 op_sel_hi:[1, 0]
	v_pk_add_f32 v[110:111], v[110:111], 0 op_sel_hi:[1, 0]
	v_lshlrev_b32_e32 v118, 16, v224
	v_and_b32_e32 v119, 0xffff0000, v224
	v_lshlrev_b32_e32 v112, 16, v225
	v_and_b32_e32 v113, 0xffff0000, v225
	v_lshlrev_b32_e32 v120, 16, v226
	v_and_b32_e32 v121, 0xffff0000, v226
	v_lshlrev_b32_e32 v114, 16, v227
	v_and_b32_e32 v115, 0xffff0000, v227
	v_pk_add_f32 v[112:113], v[108:109], v[112:113]
	v_pk_add_f32 v[92:93], v[92:93], v[118:119]
	v_pk_add_f32 v[114:115], v[110:111], v[114:115]
	v_pk_add_f32 v[110:111], v[116:117], v[120:121]
.LBB0_2347:
	v_mov_b32_e32 v108, 0
	s_and_b64 vcc, exec, s[10:11]
	v_mov_b32_e32 v116, 0
	v_mov_b32_e32 v117, 0
	v_mov_b32_e32 v120, 0
	v_mov_b32_e32 v121, 0
	v_mov_b32_e32 v118, 0
	v_mov_b32_e32 v119, 0
	v_mov_b32_e32 v122, 0
	v_mov_b32_e32 v123, 0
	s_cbranch_vccnz .LBB0_2349
	s_mov_b32 s14, 0x23000
	v_lshlrev_b32_e32 v124, 16, v212
	v_and_b32_e32 v125, 0xffff0000, v212
	v_lshlrev_b32_e32 v116, 16, v213
	v_and_b32_e32 v117, 0xffff0000, v213
	v_lshlrev_b32_e32 v126, 16, v214
	v_and_b32_e32 v127, 0xffff0000, v214
	v_lshlrev_b32_e32 v118, 16, v215
	v_and_b32_e32 v119, 0xffff0000, v215
	v_lshlrev_b32_e32 v128, 16, v216
	v_and_b32_e32 v129, 0xffff0000, v216
	v_lshlrev_b32_e32 v120, 16, v217
	v_and_b32_e32 v121, 0xffff0000, v217
	v_lshlrev_b32_e32 v130, 16, v218
	v_and_b32_e32 v131, 0xffff0000, v218
	v_lshlrev_b32_e32 v122, 16, v219
	v_and_b32_e32 v123, 0xffff0000, v219
	v_pk_add_f32 v[124:125], v[124:125], 0 op_sel_hi:[1, 0]
	v_pk_add_f32 v[116:117], v[116:117], 0 op_sel_hi:[1, 0]
	v_pk_add_f32 v[126:127], v[126:127], 0 op_sel_hi:[1, 0]
	v_pk_add_f32 v[118:119], v[118:119], 0 op_sel_hi:[1, 0]
	v_pk_add_f32 v[120:121], v[116:117], v[120:121]
	v_pk_add_f32 v[116:117], v[124:125], v[128:129]
	v_pk_add_f32 v[122:123], v[118:119], v[122:123]
	v_pk_add_f32 v[118:119], v[126:127], v[130:131]
.LBB0_2349:
	s_and_b64 vcc, exec, s[10:11]
	v_mov_b32_e32 v109, 0
	v_mov_b32_e32 v126, 0
	v_mov_b32_e32 v127, 0
	v_mov_b32_e32 v124, 0
	v_mov_b32_e32 v125, 0
	v_mov_b32_e32 v128, 0
	v_mov_b32_e32 v129, 0
	s_cbranch_vccnz .LBB0_2351
	s_mov_b32 s14, 0x23000
	v_lshlrev_b32_e32 v12, 16, v220
	v_and_b32_e32 v13, 0xffff0000, v220
	v_lshlrev_b32_e32 v108, 16, v221
	v_and_b32_e32 v109, 0xffff0000, v221
	v_lshlrev_b32_e32 v124, 16, v222
	v_and_b32_e32 v125, 0xffff0000, v222
	v_lshlrev_b32_e32 v126, 16, v223
	v_and_b32_e32 v127, 0xffff0000, v223
	v_lshlrev_b32_e32 v132, 16, v224
	v_and_b32_e32 v133, 0xffff0000, v224
	v_lshlrev_b32_e32 v128, 16, v225
	v_and_b32_e32 v129, 0xffff0000, v225
	v_lshlrev_b32_e32 v134, 16, v226
	v_and_b32_e32 v135, 0xffff0000, v226
	v_lshlrev_b32_e32 v130, 16, v227
	v_and_b32_e32 v131, 0xffff0000, v227
	v_pk_add_f32 v[12:13], v[12:13], 0 op_sel_hi:[1, 0]
	v_pk_add_f32 v[108:109], v[108:109], 0 op_sel_hi:[1, 0]
	v_pk_add_f32 v[124:125], v[124:125], 0 op_sel_hi:[1, 0]
	v_pk_add_f32 v[136:137], v[126:127], 0 op_sel_hi:[1, 0]
	v_pk_add_f32 v[126:127], v[108:109], v[128:129]
	v_pk_add_f32 v[108:109], v[12:13], v[132:133]
	v_pk_add_f32 v[128:129], v[136:137], v[130:131]
	v_pk_add_f32 v[124:125], v[124:125], v[134:135]
